# peer_act rewritten by hand: two-stage LDS-DMA prefetch of the 8 partial-hidden slices and indices, scale gathers and gate loads one iteration ahead, branch-free erf
# speedup vs baseline: 1.0191x; 1.0001x over previous
.LBB0_654:
	s_or_b64 exec, exec, s[2:3]
	s_add_u32 s48, s94, 0x3a700000
	s_addc_u32 s49, s95, 0
	s_add_u32 s50, s94, 0x3a710000
	s_addc_u32 s51, s95, 0
	s_lshl_b64 s[2:3], s[88:89], 10
	v_mov_b32_e32 v163, 0
	s_mov_b32 s97, 0
	v_lshl_add_u64 v[184:185], s[2:3], 0, v[162:163]
	s_mov_b64 s[2:3], 0x810000
	s_lshl_b64 s[52:53], s[96:97], 10
	v_cmp_gt_u64_e64 s[14:15], s[2:3], v[184:185]
	s_barrier
	s_and_saveexec_b64 s[2:3], s[14:15]
	s_cbranch_execz .LBB0_673
	v_lshrrev_b32_e32 v126, 6, v156
	s_nop 1
	v_readfirstlane_b32 s18, v126
	s_nop 3
	s_mul_i32 s18, s18, 0x4800
	s_add_u32 s23, s18, 0x2400
	v_and_b32_e32 v125, 63, v156
	v_lshlrev_b32_e32 v125, 4, v125
	v_add_u32_e32 v125, s18, v125
	s_mov_b32 s16, 16
	s_cmp_lt_u32 s88, 64
	s_cselect_b32 s16, 17, 16
	s_lshl_b32 s4, s88, 12
	v_lshlrev_b32_e32 v120, 4, v156
	v_add_u32_e32 v120, s4, v120
	s_sub_u32 s4, s16, 1
	s_lshl_b32 s4, s4, 21
	v_add_u32_e32 v121, s4, v120
	v_add_u32_e32 v123, 0x1a340000, v121
	v_add_u32_e32 v121, 0x8100000, v121
	v_add_u32_e32 v122, 0x1a340000, v120
	v_mov_b32_e32 v124, v122
	v_add_u32_e32 v120, 0x8100000, v120
	v_mov_b32_e32 v127, 0x378e98ab
	v_mov_b32_e32 v128, 0xb9c68948
	v_mov_b32_e32 v129, 0x3b7cd369
	v_mov_b32_e32 v130, 0xbcc618b2
	v_mov_b32_e32 v131, 0x3dda74e4
	v_mov_b32_e32 v132, 0x3f228afd
	v_mov_b32_e32 v133, 0x3e03c728
	v_mov_b32_e32 v134, 0x7f800000
	v_mov_b32_e32 v135, 0x3ba10414
	s_mov_b32 s19, 0xbfb8aa3b
	s_mov_b32 s20, 0x42ce8ed0
	s_mov_b32 s21, 0xc2b17218
	s_brev_b32 s22, -2
	s_add_u32 s24, s94, 0x3a700000
	s_addc_u32 s25, s95, 0
	s_add_u32 s26, s94, 0x3a710000
	s_addc_u32 s27, s95, 0
	s_add_u32 m0, s18, 0x0
	v_mov_b32_e32 v126, v120
	global_load_lds_dwordx4 v126, s[94:95]
	s_add_u32 m0, s18, 0x400
	v_add_u32_e32 v126, 0x2040000, v120
	global_load_lds_dwordx4 v126, s[94:95]
	s_add_u32 m0, s18, 0x800
	v_add_u32_e32 v126, 0x4080000, v120
	global_load_lds_dwordx4 v126, s[94:95]
	s_add_u32 m0, s18, 0xc00
	v_add_u32_e32 v126, 0x60c0000, v120
	global_load_lds_dwordx4 v126, s[94:95]
	s_add_u32 m0, s18, 0x1000
	v_add_u32_e32 v126, 0x8100000, v120
	global_load_lds_dwordx4 v126, s[94:95]
	s_add_u32 m0, s18, 0x1400
	v_add_u32_e32 v126, 0xa140000, v120
	global_load_lds_dwordx4 v126, s[94:95]
	s_add_u32 m0, s18, 0x1800
	v_add_u32_e32 v126, 0xc180000, v120
	global_load_lds_dwordx4 v126, s[94:95]
	s_add_u32 m0, s18, 0x1c00
	v_add_u32_e32 v126, 0xe1c0000, v120
	global_load_lds_dwordx4 v126, s[94:95]
	s_add_u32 m0, s18, 0x2000
	v_add_u32_e32 v126, 0x10200000, v120
	global_load_lds_dwordx4 v126, s[94:95]
	v_add_u32_e32 v120, 0x200000, v120
	v_min_u32_e32 v120, v120, v121
	s_add_u32 m0, s23, 0x0
	v_mov_b32_e32 v126, v120
	global_load_lds_dwordx4 v126, s[94:95]
	s_add_u32 m0, s23, 0x400
	v_add_u32_e32 v126, 0x2040000, v120
	global_load_lds_dwordx4 v126, s[94:95]
	s_add_u32 m0, s23, 0x800
	v_add_u32_e32 v126, 0x4080000, v120
	global_load_lds_dwordx4 v126, s[94:95]
	s_add_u32 m0, s23, 0xc00
	v_add_u32_e32 v126, 0x60c0000, v120
	global_load_lds_dwordx4 v126, s[94:95]
	s_add_u32 m0, s23, 0x1000
	v_add_u32_e32 v126, 0x8100000, v120
	global_load_lds_dwordx4 v126, s[94:95]
	s_add_u32 m0, s23, 0x1400
	v_add_u32_e32 v126, 0xa140000, v120
	global_load_lds_dwordx4 v126, s[94:95]
	s_add_u32 m0, s23, 0x1800
	v_add_u32_e32 v126, 0xc180000, v120
	global_load_lds_dwordx4 v126, s[94:95]
	s_add_u32 m0, s23, 0x1c00
	v_add_u32_e32 v126, 0xe1c0000, v120
	global_load_lds_dwordx4 v126, s[94:95]
	s_add_u32 m0, s23, 0x2000
	v_add_u32_e32 v126, 0x10200000, v120
	global_load_lds_dwordx4 v126, s[94:95]
	v_add_u32_e32 v120, 0x200000, v120
	v_min_u32_e32 v120, v120, v121
	s_waitcnt vmcnt(9)
	ds_read_b128 v[0:3], v125 offset:0
	ds_read_b128 v[4:7], v125 offset:1024
	ds_read_b128 v[8:11], v125 offset:2048
	ds_read_b128 v[12:15], v125 offset:3072
	ds_read_b128 v[16:19], v125 offset:4096
	ds_read_b128 v[20:23], v125 offset:5120
	ds_read_b128 v[24:27], v125 offset:6144
	ds_read_b128 v[28:31], v125 offset:7168
	ds_read_b128 v[64:67], v125 offset:8192
	s_waitcnt lgkmcnt(0)
	v_lshlrev_b32_e32 v64, 2, v64
	v_lshlrev_b32_e32 v65, 2, v65
	v_lshlrev_b32_e32 v66, 2, v66
	v_lshlrev_b32_e32 v67, 2, v67
	global_load_dword v68, v64, s[24:25]
	global_load_dword v69, v65, s[24:25]
	global_load_dword v70, v66, s[24:25]
	global_load_dword v71, v67, s[24:25]
	global_load_dword v72, v64, s[26:27]
	global_load_dword v73, v65, s[26:27]
	global_load_dword v74, v66, s[26:27]
	global_load_dword v75, v67, s[26:27]
	global_load_dwordx4 v[84:87], v122, s[94:95]
	v_add_u32_e32 v122, 0x200000, v122
	v_min_u32_e32 v122, v122, v123
	s_add_u32 m0, s18, 0x0
	v_mov_b32_e32 v126, v120
	global_load_lds_dwordx4 v126, s[94:95]
	s_add_u32 m0, s18, 0x400
	v_add_u32_e32 v126, 0x2040000, v120
	global_load_lds_dwordx4 v126, s[94:95]
	s_add_u32 m0, s18, 0x800
	v_add_u32_e32 v126, 0x4080000, v120
	global_load_lds_dwordx4 v126, s[94:95]
	s_add_u32 m0, s18, 0xc00
	v_add_u32_e32 v126, 0x60c0000, v120
	global_load_lds_dwordx4 v126, s[94:95]
	s_add_u32 m0, s18, 0x1000
	v_add_u32_e32 v126, 0x8100000, v120
	global_load_lds_dwordx4 v126, s[94:95]
	s_add_u32 m0, s18, 0x1400
	v_add_u32_e32 v126, 0xa140000, v120
	global_load_lds_dwordx4 v126, s[94:95]
	s_add_u32 m0, s18, 0x1800
	v_add_u32_e32 v126, 0xc180000, v120
	global_load_lds_dwordx4 v126, s[94:95]
	s_add_u32 m0, s18, 0x1c00
	v_add_u32_e32 v126, 0xe1c0000, v120
	global_load_lds_dwordx4 v126, s[94:95]
	s_add_u32 m0, s18, 0x2000
	v_add_u32_e32 v126, 0x10200000, v120
	global_load_lds_dwordx4 v126, s[94:95]
	v_add_u32_e32 v120, 0x200000, v120
	v_min_u32_e32 v120, v120, v121
	global_load_dword v137, v124, s[94:95]
	s_mov_b32 s17, 0
	s_waitcnt vmcnt(19)
.Lact0_loop:
	s_waitcnt vmcnt(20)
	ds_read_b128 v[32:35], v125 offset:9216
	ds_read_b128 v[36:39], v125 offset:10240
	ds_read_b128 v[40:43], v125 offset:11264
	ds_read_b128 v[44:47], v125 offset:12288
	ds_read_b128 v[48:51], v125 offset:13312
	ds_read_b128 v[52:55], v125 offset:14336
	ds_read_b128 v[56:59], v125 offset:15360
	ds_read_b128 v[60:63], v125 offset:16384
	ds_read_b128 v[64:67], v125 offset:17408
	s_waitcnt lgkmcnt(0)
	v_lshlrev_b32_e32 v64, 2, v64
	v_lshlrev_b32_e32 v65, 2, v65
	v_lshlrev_b32_e32 v66, 2, v66
	v_lshlrev_b32_e32 v67, 2, v67
	global_load_dword v76, v64, s[24:25]
	global_load_dword v77, v65, s[24:25]
	global_load_dword v78, v66, s[24:25]
	global_load_dword v79, v67, s[24:25]
	global_load_dword v80, v64, s[26:27]
	global_load_dword v81, v65, s[26:27]
	global_load_dword v82, v66, s[26:27]
	global_load_dword v83, v67, s[26:27]
	global_load_dwordx4 v[88:91], v122, s[94:95]
	v_add_u32_e32 v122, 0x200000, v122
	v_min_u32_e32 v122, v122, v123
	s_add_u32 m0, s23, 0x0
	v_mov_b32_e32 v126, v120
	global_load_lds_dwordx4 v126, s[94:95]
	s_add_u32 m0, s23, 0x400
	v_add_u32_e32 v126, 0x2040000, v120
	global_load_lds_dwordx4 v126, s[94:95]
	s_add_u32 m0, s23, 0x800
	v_add_u32_e32 v126, 0x4080000, v120
	global_load_lds_dwordx4 v126, s[94:95]
	s_add_u32 m0, s23, 0xc00
	v_add_u32_e32 v126, 0x60c0000, v120
	global_load_lds_dwordx4 v126, s[94:95]
	s_add_u32 m0, s23, 0x1000
	v_add_u32_e32 v126, 0x8100000, v120
	global_load_lds_dwordx4 v126, s[94:95]
	s_add_u32 m0, s23, 0x1400
	v_add_u32_e32 v126, 0xa140000, v120
	global_load_lds_dwordx4 v126, s[94:95]
	s_add_u32 m0, s23, 0x1800
	v_add_u32_e32 v126, 0xc180000, v120
	global_load_lds_dwordx4 v126, s[94:95]
	s_add_u32 m0, s23, 0x1c00
	v_add_u32_e32 v126, 0xe1c0000, v120
	global_load_lds_dwordx4 v126, s[94:95]
	s_add_u32 m0, s23, 0x2000
	v_add_u32_e32 v126, 0x10200000, v120
	global_load_lds_dwordx4 v126, s[94:95]
	v_add_u32_e32 v120, 0x200000, v120
	v_min_u32_e32 v120, v120, v121
	s_waitcnt vmcnt(28)
	v_add_f32_e32 v92, 0, v0
	v_add_f32_e32 v99, 0, v1
	v_add_f32_e32 v106, 0, v2
	v_add_f32_e32 v113, 0, v3
	v_add_f32_e32 v92, v92, v4
	v_add_f32_e32 v99, v99, v5
	v_add_f32_e32 v106, v106, v6
	v_add_f32_e32 v113, v113, v7
	v_add_f32_e32 v92, v92, v8
	v_add_f32_e32 v99, v99, v9
	v_add_f32_e32 v106, v106, v10
	v_add_f32_e32 v113, v113, v11
	v_add_f32_e32 v92, v92, v12
	v_add_f32_e32 v99, v99, v13
	v_add_f32_e32 v106, v106, v14
	v_add_f32_e32 v113, v113, v15
	v_add_f32_e32 v92, v92, v16
	v_add_f32_e32 v99, v99, v17
	v_add_f32_e32 v106, v106, v18
	v_add_f32_e32 v113, v113, v19
	v_add_f32_e32 v92, v92, v20
	v_add_f32_e32 v99, v99, v21
	v_add_f32_e32 v106, v106, v22
	v_add_f32_e32 v113, v113, v23
	v_add_f32_e32 v92, v92, v24
	v_add_f32_e32 v99, v99, v25
	v_add_f32_e32 v106, v106, v26
	v_add_f32_e32 v113, v113, v27
	v_add_f32_e32 v92, v92, v28
	v_add_f32_e32 v99, v99, v29
	v_add_f32_e32 v106, v106, v30
	v_add_f32_e32 v113, v113, v31
	v_mul_f32_e32 v92, v92, v68
	v_mul_f32_e32 v99, v99, v69
	v_mul_f32_e32 v106, v106, v70
	v_mul_f32_e32 v113, v113, v71
	v_mul_f32_e32 v93, 0x3f3504f3, v92
	v_mul_f32_e32 v100, 0x3f3504f3, v99
	v_mul_f32_e32 v107, 0x3f3504f3, v106
	v_mul_f32_e32 v114, 0x3f3504f3, v113
	v_fma_f32 v94, |v93|, v127, v128
	v_fma_f32 v101, |v100|, v127, v128
	v_fma_f32 v108, |v107|, v127, v128
	v_fma_f32 v115, |v114|, v127, v128
	v_fma_f32 v94, |v93|, v94, v129
	v_fma_f32 v101, |v100|, v101, v129
	v_fma_f32 v108, |v107|, v108, v129
	v_fma_f32 v115, |v114|, v115, v129
	v_fma_f32 v94, |v93|, v94, v130
	v_fma_f32 v101, |v100|, v101, v130
	v_fma_f32 v108, |v107|, v108, v130
	v_fma_f32 v115, |v114|, v115, v130
	v_fma_f32 v94, |v93|, v94, v131
	v_fma_f32 v101, |v100|, v101, v131
	v_fma_f32 v108, |v107|, v108, v131
	v_fma_f32 v115, |v114|, v115, v131
	v_fma_f32 v94, |v93|, v94, v132
	v_fma_f32 v101, |v100|, v101, v132
	v_fma_f32 v108, |v107|, v108, v132
	v_fma_f32 v115, |v114|, v115, v132
	v_fma_f32 v94, |v93|, v94, v133
	v_fma_f32 v101, |v100|, v101, v133
	v_fma_f32 v108, |v107|, v108, v133
	v_fma_f32 v115, |v114|, v115, v133
	v_fma_f32 v94, |v93|, v94, |v93|
	v_fma_f32 v101, |v100|, v101, |v100|
	v_fma_f32 v108, |v107|, v108, |v107|
	v_fma_f32 v115, |v114|, v115, |v114|
	v_mul_f32_e32 v96, s19, v94
	v_mul_f32_e32 v103, s19, v101
	v_mul_f32_e32 v110, s19, v108
	v_mul_f32_e32 v117, s19, v115
	v_fma_f32 v97, v94, s19, -v96
	v_fma_f32 v104, v101, s19, -v103
	v_fma_f32 v111, v108, s19, -v110
	v_fma_f32 v118, v115, s19, -v117
	v_rndne_f32_e32 v98, v96
	v_rndne_f32_e32 v105, v103
	v_rndne_f32_e32 v112, v110
	v_rndne_f32_e32 v119, v117
	v_fmac_f32_e32 v97, 0xb2a5705f, v94
	v_fmac_f32_e32 v104, 0xb2a5705f, v101
	v_fmac_f32_e32 v111, 0xb2a5705f, v108
	v_fmac_f32_e32 v118, 0xb2a5705f, v115
	v_sub_f32_e32 v96, v96, v98
	v_sub_f32_e32 v103, v103, v105
	v_sub_f32_e32 v110, v110, v112
	v_sub_f32_e32 v117, v117, v119
	v_add_f32_e32 v96, v96, v97
	v_add_f32_e32 v103, v103, v104
	v_add_f32_e32 v110, v110, v111
	v_add_f32_e32 v117, v117, v118
	v_cvt_i32_f32_e32 v98, v98
	v_cvt_i32_f32_e32 v105, v105
	v_cvt_i32_f32_e32 v112, v112
	v_cvt_i32_f32_e32 v119, v119
	v_exp_f32_e32 v96, v96
	v_exp_f32_e32 v103, v103
	v_exp_f32_e32 v110, v110
	v_exp_f32_e32 v117, v117
	v_cmp_nlt_f32_e64 s[4:5], s20, v94
	v_cmp_nlt_f32_e64 s[98:99], s20, v101
	v_cmp_nlt_f32_e64 s[100:101], s20, v108
	v_cmp_nlt_f32_e64 vcc, s20, v115
	v_ldexp_f32 v96, v96, v98
	v_ldexp_f32 v103, v103, v105
	v_ldexp_f32 v110, v110, v112
	v_ldexp_f32 v117, v117, v119
	v_mul_f32_e32 v95, v93, v93
	v_mul_f32_e32 v102, v100, v100
	v_mul_f32_e32 v109, v107, v107
	v_mul_f32_e32 v116, v114, v114
	v_cndmask_b32_e64 v96, 0, v96, s[4:5]
	v_cndmask_b32_e64 v103, 0, v103, s[98:99]
	v_cndmask_b32_e64 v110, 0, v110, s[100:101]
	v_cndmask_b32_e64 v117, 0, v117, vcc
	v_cmp_ngt_f32_e64 s[4:5], s21, v94
	v_cmp_ngt_f32_e64 s[98:99], s21, v101
	v_cmp_ngt_f32_e64 s[100:101], s21, v108
	v_cmp_ngt_f32_e64 vcc, s21, v115
	v_fmamk_f32 v97, v95, 0xba1345e1, v135
	v_fmamk_f32 v104, v102, 0xba1345e1, v135
	v_fmamk_f32 v111, v109, 0xba1345e1, v135
	v_fmamk_f32 v118, v116, 0xba1345e1, v135
	v_fmaak_f32 v97, v95, v97, 0xbcdac9b8
	v_fmaak_f32 v104, v102, v104, 0xbcdac9b8
	v_fmaak_f32 v111, v109, v111, 0xbcdac9b8
	v_fmaak_f32 v118, v116, v118, 0xbcdac9b8
	v_cndmask_b32_e64 v96, v134, v96, s[4:5]
	v_cndmask_b32_e64 v103, v134, v103, s[98:99]
	v_cndmask_b32_e64 v110, v134, v110, s[100:101]
	v_cndmask_b32_e64 v117, v134, v117, vcc
	v_fmaak_f32 v97, v95, v97, 0x3de703be
	v_fmaak_f32 v104, v102, v104, 0x3de703be
	v_fmaak_f32 v111, v109, v111, 0x3de703be
	v_fmaak_f32 v118, v116, v118, 0x3de703be
	v_fmaak_f32 v97, v95, v97, 0xbec09330
	v_fmaak_f32 v104, v102, v104, 0xbec09330
	v_fmaak_f32 v111, v109, v111, 0xbec09330
	v_fmaak_f32 v118, v116, v118, 0xbec09330
	v_sub_f32_e32 v96, 1.0, v96
	v_sub_f32_e32 v103, 1.0, v103
	v_sub_f32_e32 v110, 1.0, v110
	v_sub_f32_e32 v117, 1.0, v117
	v_fmaak_f32 v97, v95, v97, 0x3e0375d0
	v_fmaak_f32 v104, v102, v104, 0x3e0375d0
	v_fmaak_f32 v111, v109, v111, 0x3e0375d0
	v_fmaak_f32 v118, v116, v118, 0x3e0375d0
	v_cmp_nlt_f32_e64 s[4:5], |v93|, 1.0
	v_cmp_nlt_f32_e64 s[98:99], |v100|, 1.0
	v_cmp_nlt_f32_e64 s[100:101], |v107|, 1.0
	v_cmp_nlt_f32_e64 vcc, |v114|, 1.0
	v_fma_f32 v97, |v93|, v97, |v93|
	v_fma_f32 v104, |v100|, v104, |v100|
	v_fma_f32 v111, |v107|, v111, |v107|
	v_fma_f32 v118, |v114|, v118, |v114|
	v_mul_f32_e32 v92, 0.5, v92
	v_mul_f32_e32 v99, 0.5, v99
	v_mul_f32_e32 v106, 0.5, v106
	v_mul_f32_e32 v113, 0.5, v113
	v_mul_f32_e32 v95, v84, v72
	v_mul_f32_e32 v102, v85, v73
	v_mul_f32_e32 v109, v86, v74
	v_mul_f32_e32 v116, v87, v75
	v_cndmask_b32_e64 v96, v97, v96, s[4:5]
	v_cndmask_b32_e64 v103, v104, v103, s[98:99]
	v_cndmask_b32_e64 v110, v111, v110, s[100:101]
	v_cndmask_b32_e64 v117, v118, v117, vcc
	v_bfi_b32 v96, s22, v96, v93
	v_bfi_b32 v103, s22, v103, v100
	v_bfi_b32 v110, s22, v110, v107
	v_bfi_b32 v117, s22, v117, v114
	v_add_f32_e32 v96, 1.0, v96
	v_add_f32_e32 v103, 1.0, v103
	v_add_f32_e32 v110, 1.0, v110
	v_add_f32_e32 v117, 1.0, v117
	v_mul_f32_e32 v92, v92, v96
	v_mul_f32_e32 v99, v99, v103
	v_mul_f32_e32 v106, v106, v110
	v_mul_f32_e32 v113, v113, v117
	v_mul_f32_e32 v92, v84, v92
	v_mul_f32_e32 v99, v85, v99
	v_mul_f32_e32 v106, v86, v106
	v_mul_f32_e32 v113, v87, v113
	v_mul_f32_e32 v92, v72, v92
	v_mul_f32_e32 v99, v73, v99
	v_mul_f32_e32 v106, v74, v106
	v_mul_f32_e32 v113, v75, v113
	v_mov_b32_e32 v64, v92
	v_mov_b32_e32 v65, v99
	v_mov_b32_e32 v66, v106
	v_mov_b32_e32 v67, v113
	global_store_dwordx4 v124, v[64:67], s[94:95]
	v_add_u32_e32 v124, 0x200000, v124
	s_add_u32 s17, s17, 1
	s_cmp_lt_u32 s17, s16
	s_cbranch_scc0 .Lact0_done
	s_waitcnt vmcnt(20)
	ds_read_b128 v[0:3], v125 offset:0
	ds_read_b128 v[4:7], v125 offset:1024
	ds_read_b128 v[8:11], v125 offset:2048
	ds_read_b128 v[12:15], v125 offset:3072
	ds_read_b128 v[16:19], v125 offset:4096
	ds_read_b128 v[20:23], v125 offset:5120
	ds_read_b128 v[24:27], v125 offset:6144
	ds_read_b128 v[28:31], v125 offset:7168
	ds_read_b128 v[64:67], v125 offset:8192
	s_waitcnt lgkmcnt(0)
	v_lshlrev_b32_e32 v64, 2, v64
	v_lshlrev_b32_e32 v65, 2, v65
	v_lshlrev_b32_e32 v66, 2, v66
	v_lshlrev_b32_e32 v67, 2, v67
	global_load_dword v68, v64, s[24:25]
	global_load_dword v69, v65, s[24:25]
	global_load_dword v70, v66, s[24:25]
	global_load_dword v71, v67, s[24:25]
	global_load_dword v72, v64, s[26:27]
	global_load_dword v73, v65, s[26:27]
	global_load_dword v74, v66, s[26:27]
	global_load_dword v75, v67, s[26:27]
	global_load_dwordx4 v[84:87], v122, s[94:95]
	v_add_u32_e32 v122, 0x200000, v122
	v_min_u32_e32 v122, v122, v123
	s_add_u32 m0, s18, 0x0
	v_mov_b32_e32 v126, v120
	global_load_lds_dwordx4 v126, s[94:95]
	s_add_u32 m0, s18, 0x400
	v_add_u32_e32 v126, 0x2040000, v120
	global_load_lds_dwordx4 v126, s[94:95]
	s_add_u32 m0, s18, 0x800
	v_add_u32_e32 v126, 0x4080000, v120
	global_load_lds_dwordx4 v126, s[94:95]
	s_add_u32 m0, s18, 0xc00
	v_add_u32_e32 v126, 0x60c0000, v120
	global_load_lds_dwordx4 v126, s[94:95]
	s_add_u32 m0, s18, 0x1000
	v_add_u32_e32 v126, 0x8100000, v120
	global_load_lds_dwordx4 v126, s[94:95]
	s_add_u32 m0, s18, 0x1400
	v_add_u32_e32 v126, 0xa140000, v120
	global_load_lds_dwordx4 v126, s[94:95]
	s_add_u32 m0, s18, 0x1800
	v_add_u32_e32 v126, 0xc180000, v120
	global_load_lds_dwordx4 v126, s[94:95]
	s_add_u32 m0, s18, 0x1c00
	v_add_u32_e32 v126, 0xe1c0000, v120
	global_load_lds_dwordx4 v126, s[94:95]
	s_add_u32 m0, s18, 0x2000
	v_add_u32_e32 v126, 0x10200000, v120
	global_load_lds_dwordx4 v126, s[94:95]
	v_add_u32_e32 v120, 0x200000, v120
	v_min_u32_e32 v120, v120, v121
	s_waitcnt vmcnt(28)
	v_add_f32_e32 v92, 0, v32
	v_add_f32_e32 v99, 0, v33
	v_add_f32_e32 v106, 0, v34
	v_add_f32_e32 v113, 0, v35
	v_add_f32_e32 v92, v92, v36
	v_add_f32_e32 v99, v99, v37
	v_add_f32_e32 v106, v106, v38
	v_add_f32_e32 v113, v113, v39
	v_add_f32_e32 v92, v92, v40
	v_add_f32_e32 v99, v99, v41
	v_add_f32_e32 v106, v106, v42
	v_add_f32_e32 v113, v113, v43
	v_add_f32_e32 v92, v92, v44
	v_add_f32_e32 v99, v99, v45
	v_add_f32_e32 v106, v106, v46
	v_add_f32_e32 v113, v113, v47
	v_add_f32_e32 v92, v92, v48
	v_add_f32_e32 v99, v99, v49
	v_add_f32_e32 v106, v106, v50
	v_add_f32_e32 v113, v113, v51
	v_add_f32_e32 v92, v92, v52
	v_add_f32_e32 v99, v99, v53
	v_add_f32_e32 v106, v106, v54
	v_add_f32_e32 v113, v113, v55
	v_add_f32_e32 v92, v92, v56
	v_add_f32_e32 v99, v99, v57
	v_add_f32_e32 v106, v106, v58
	v_add_f32_e32 v113, v113, v59
	v_add_f32_e32 v92, v92, v60
	v_add_f32_e32 v99, v99, v61
	v_add_f32_e32 v106, v106, v62
	v_add_f32_e32 v113, v113, v63
	v_mul_f32_e32 v92, v92, v76
	v_mul_f32_e32 v99, v99, v77
	v_mul_f32_e32 v106, v106, v78
	v_mul_f32_e32 v113, v113, v79
	v_mul_f32_e32 v93, 0x3f3504f3, v92
	v_mul_f32_e32 v100, 0x3f3504f3, v99
	v_mul_f32_e32 v107, 0x3f3504f3, v106
	v_mul_f32_e32 v114, 0x3f3504f3, v113
	v_fma_f32 v94, |v93|, v127, v128
	v_fma_f32 v101, |v100|, v127, v128
	v_fma_f32 v108, |v107|, v127, v128
	v_fma_f32 v115, |v114|, v127, v128
	v_fma_f32 v94, |v93|, v94, v129
	v_fma_f32 v101, |v100|, v101, v129
	v_fma_f32 v108, |v107|, v108, v129
	v_fma_f32 v115, |v114|, v115, v129
	v_fma_f32 v94, |v93|, v94, v130
	v_fma_f32 v101, |v100|, v101, v130
	v_fma_f32 v108, |v107|, v108, v130
	v_fma_f32 v115, |v114|, v115, v130
	v_fma_f32 v94, |v93|, v94, v131
	v_fma_f32 v101, |v100|, v101, v131
	v_fma_f32 v108, |v107|, v108, v131
	v_fma_f32 v115, |v114|, v115, v131
	v_fma_f32 v94, |v93|, v94, v132
	v_fma_f32 v101, |v100|, v101, v132
	v_fma_f32 v108, |v107|, v108, v132
	v_fma_f32 v115, |v114|, v115, v132
	v_fma_f32 v94, |v93|, v94, v133
	v_fma_f32 v101, |v100|, v101, v133
	v_fma_f32 v108, |v107|, v108, v133
	v_fma_f32 v115, |v114|, v115, v133
	v_fma_f32 v94, |v93|, v94, |v93|
	v_fma_f32 v101, |v100|, v101, |v100|
	v_fma_f32 v108, |v107|, v108, |v107|
	v_fma_f32 v115, |v114|, v115, |v114|
	v_mul_f32_e32 v96, s19, v94
	v_mul_f32_e32 v103, s19, v101
	v_mul_f32_e32 v110, s19, v108
	v_mul_f32_e32 v117, s19, v115
	v_fma_f32 v97, v94, s19, -v96
	v_fma_f32 v104, v101, s19, -v103
	v_fma_f32 v111, v108, s19, -v110
	v_fma_f32 v118, v115, s19, -v117
	v_rndne_f32_e32 v98, v96
	v_rndne_f32_e32 v105, v103
	v_rndne_f32_e32 v112, v110
	v_rndne_f32_e32 v119, v117
	v_fmac_f32_e32 v97, 0xb2a5705f, v94
	v_fmac_f32_e32 v104, 0xb2a5705f, v101
	v_fmac_f32_e32 v111, 0xb2a5705f, v108
	v_fmac_f32_e32 v118, 0xb2a5705f, v115
	v_sub_f32_e32 v96, v96, v98
	v_sub_f32_e32 v103, v103, v105
	v_sub_f32_e32 v110, v110, v112
	v_sub_f32_e32 v117, v117, v119
	v_add_f32_e32 v96, v96, v97
	v_add_f32_e32 v103, v103, v104
	v_add_f32_e32 v110, v110, v111
	v_add_f32_e32 v117, v117, v118
	v_cvt_i32_f32_e32 v98, v98
	v_cvt_i32_f32_e32 v105, v105
	v_cvt_i32_f32_e32 v112, v112
	v_cvt_i32_f32_e32 v119, v119
	v_exp_f32_e32 v96, v96
	v_exp_f32_e32 v103, v103
	v_exp_f32_e32 v110, v110
	v_exp_f32_e32 v117, v117
	v_cmp_nlt_f32_e64 s[4:5], s20, v94
	v_cmp_nlt_f32_e64 s[98:99], s20, v101
	v_cmp_nlt_f32_e64 s[100:101], s20, v108
	v_cmp_nlt_f32_e64 vcc, s20, v115
	v_ldexp_f32 v96, v96, v98
	v_ldexp_f32 v103, v103, v105
	v_ldexp_f32 v110, v110, v112
	v_ldexp_f32 v117, v117, v119
	v_mul_f32_e32 v95, v93, v93
	v_mul_f32_e32 v102, v100, v100
	v_mul_f32_e32 v109, v107, v107
	v_mul_f32_e32 v116, v114, v114
	v_cndmask_b32_e64 v96, 0, v96, s[4:5]
	v_cndmask_b32_e64 v103, 0, v103, s[98:99]
	v_cndmask_b32_e64 v110, 0, v110, s[100:101]
	v_cndmask_b32_e64 v117, 0, v117, vcc
	v_cmp_ngt_f32_e64 s[4:5], s21, v94
	v_cmp_ngt_f32_e64 s[98:99], s21, v101
	v_cmp_ngt_f32_e64 s[100:101], s21, v108
	v_cmp_ngt_f32_e64 vcc, s21, v115
	v_fmamk_f32 v97, v95, 0xba1345e1, v135
	v_fmamk_f32 v104, v102, 0xba1345e1, v135
	v_fmamk_f32 v111, v109, 0xba1345e1, v135
	v_fmamk_f32 v118, v116, 0xba1345e1, v135
	v_fmaak_f32 v97, v95, v97, 0xbcdac9b8
	v_fmaak_f32 v104, v102, v104, 0xbcdac9b8
	v_fmaak_f32 v111, v109, v111, 0xbcdac9b8
	v_fmaak_f32 v118, v116, v118, 0xbcdac9b8
	v_cndmask_b32_e64 v96, v134, v96, s[4:5]
	v_cndmask_b32_e64 v103, v134, v103, s[98:99]
	v_cndmask_b32_e64 v110, v134, v110, s[100:101]
	v_cndmask_b32_e64 v117, v134, v117, vcc
	v_fmaak_f32 v97, v95, v97, 0x3de703be
	v_fmaak_f32 v104, v102, v104, 0x3de703be
	v_fmaak_f32 v111, v109, v111, 0x3de703be
	v_fmaak_f32 v118, v116, v118, 0x3de703be
	v_fmaak_f32 v97, v95, v97, 0xbec09330
	v_fmaak_f32 v104, v102, v104, 0xbec09330
	v_fmaak_f32 v111, v109, v111, 0xbec09330
	v_fmaak_f32 v118, v116, v118, 0xbec09330
	v_sub_f32_e32 v96, 1.0, v96
	v_sub_f32_e32 v103, 1.0, v103
	v_sub_f32_e32 v110, 1.0, v110
	v_sub_f32_e32 v117, 1.0, v117
	v_fmaak_f32 v97, v95, v97, 0x3e0375d0
	v_fmaak_f32 v104, v102, v104, 0x3e0375d0
	v_fmaak_f32 v111, v109, v111, 0x3e0375d0
	v_fmaak_f32 v118, v116, v118, 0x3e0375d0
	v_cmp_nlt_f32_e64 s[4:5], |v93|, 1.0
	v_cmp_nlt_f32_e64 s[98:99], |v100|, 1.0
	v_cmp_nlt_f32_e64 s[100:101], |v107|, 1.0
	v_cmp_nlt_f32_e64 vcc, |v114|, 1.0
	v_fma_f32 v97, |v93|, v97, |v93|
	v_fma_f32 v104, |v100|, v104, |v100|
	v_fma_f32 v111, |v107|, v111, |v107|
	v_fma_f32 v118, |v114|, v118, |v114|
	v_mul_f32_e32 v92, 0.5, v92
	v_mul_f32_e32 v99, 0.5, v99
	v_mul_f32_e32 v106, 0.5, v106
	v_mul_f32_e32 v113, 0.5, v113
	v_mul_f32_e32 v95, v88, v80
	v_mul_f32_e32 v102, v89, v81
	v_mul_f32_e32 v109, v90, v82
	v_mul_f32_e32 v116, v91, v83
	v_cndmask_b32_e64 v96, v97, v96, s[4:5]
	v_cndmask_b32_e64 v103, v104, v103, s[98:99]
	v_cndmask_b32_e64 v110, v111, v110, s[100:101]
	v_cndmask_b32_e64 v117, v118, v117, vcc
	v_bfi_b32 v96, s22, v96, v93
	v_bfi_b32 v103, s22, v103, v100
	v_bfi_b32 v110, s22, v110, v107
	v_bfi_b32 v117, s22, v117, v114
	v_add_f32_e32 v96, 1.0, v96
	v_add_f32_e32 v103, 1.0, v103
	v_add_f32_e32 v110, 1.0, v110
	v_add_f32_e32 v117, 1.0, v117
	v_mul_f32_e32 v92, v92, v96
	v_mul_f32_e32 v99, v99, v103
	v_mul_f32_e32 v106, v106, v110
	v_mul_f32_e32 v113, v113, v117
	v_mul_f32_e32 v92, v88, v92
	v_mul_f32_e32 v99, v89, v99
	v_mul_f32_e32 v106, v90, v106
	v_mul_f32_e32 v113, v91, v113
	v_mul_f32_e32 v92, v80, v92
	v_mul_f32_e32 v99, v81, v99
	v_mul_f32_e32 v106, v82, v106
	v_mul_f32_e32 v113, v83, v113
	v_mov_b32_e32 v64, v92
	v_mov_b32_e32 v65, v99
	v_mov_b32_e32 v66, v106
	v_mov_b32_e32 v67, v113
	global_store_dwordx4 v124, v[64:67], s[94:95]
	v_add_u32_e32 v124, 0x200000, v124
	s_add_u32 s17, s17, 1
	s_cmp_lt_u32 s17, s16
	s_cbranch_scc1 .Lact0_loop
.Lact0_done:
	s_waitcnt vmcnt(0) lgkmcnt(0)
.LBB0_673:
	s_or_b64 exec, exec, s[2:3]
	s_waitcnt vmcnt(0) lgkmcnt(0)
	s_barrier
	s_mov_b64 s[2:3], exec
	v_readlane_b32 s4, v252, 31
	v_readlane_b32 s5, v252, 32
	s_and_b64 s[4:5], s[2:3], s[4:5]
	s_mov_b64 exec, s[4:5]
	s_cbranch_execz .LBB0_679
	s_mov_b64 s[4:5], exec
	buffer_wbl2 sc1
	s_waitcnt vmcnt(0)
	s_waitcnt vmcnt(0)
	v_mbcnt_lo_u32_b32 v0, s4, 0
	v_mbcnt_hi_u32_b32 v0, s5, v0
	v_cmp_eq_u32_e32 vcc, 0, v0
	s_and_saveexec_b64 s[16:17], vcc
	s_cbranch_execz .LBB0_676
	s_bcnt1_i32_b64 s4, s[4:5]
	s_and_b32 s98, s88, 7
	s_lshl_b32 s98, s98, 8
	s_add_u32 s98, s98, 0x3c6f0000
	v_mov_b32_e32 v0, s98
	v_mov_b32_e32 v1, s4
	global_atomic_add v1, v0, v1, s[94:95] sc0

.LBB0_1116:
	s_or_b64 exec, exec, s[0:1]
	s_barrier
	s_and_saveexec_b64 s[0:1], s[14:15]
	s_cbranch_execz .LBB0_1135
	v_lshrrev_b32_e32 v126, 6, v156
	s_nop 1
	v_readfirstlane_b32 s18, v126
	s_nop 3
	s_mul_i32 s18, s18, 0x4800
	s_add_u32 s23, s18, 0x2400
	v_and_b32_e32 v125, 63, v156
	v_lshlrev_b32_e32 v125, 4, v125
	v_add_u32_e32 v125, s18, v125
	s_mov_b32 s16, 16
	s_cmp_lt_u32 s88, 64
	s_cselect_b32 s16, 17, 16
	s_lshl_b32 s4, s88, 12
	v_lshlrev_b32_e32 v120, 4, v156
	v_add_u32_e32 v120, s4, v120
	s_sub_u32 s4, s16, 1
	s_lshl_b32 s4, s4, 21
	v_add_u32_e32 v121, s4, v120
	v_add_u32_e32 v123, 0x1a340000, v121
	v_add_u32_e32 v121, 0x8100000, v121
	v_add_u32_e32 v122, 0x1a340000, v120
	v_mov_b32_e32 v124, v122
	v_add_u32_e32 v120, 0x8100000, v120
	v_mov_b32_e32 v127, 0x378e98ab
	v_mov_b32_e32 v128, 0xb9c68948
	v_mov_b32_e32 v129, 0x3b7cd369
	v_mov_b32_e32 v130, 0xbcc618b2
	v_mov_b32_e32 v131, 0x3dda74e4
	v_mov_b32_e32 v132, 0x3f228afd
	v_mov_b32_e32 v133, 0x3e03c728
	v_mov_b32_e32 v134, 0x7f800000
	v_mov_b32_e32 v135, 0x3ba10414
	s_mov_b32 s19, 0xbfb8aa3b
	s_mov_b32 s20, 0x42ce8ed0
	s_mov_b32 s21, 0xc2b17218
	s_brev_b32 s22, -2
	s_add_u32 s24, s94, 0x3a700000
	s_addc_u32 s25, s95, 0
	s_add_u32 s26, s94, 0x3a710000
	s_addc_u32 s27, s95, 0
	s_add_u32 m0, s18, 0x0
	v_mov_b32_e32 v126, v120
	global_load_lds_dwordx4 v126, s[94:95]
	s_add_u32 m0, s18, 0x400
	v_add_u32_e32 v126, 0x2040000, v120
	global_load_lds_dwordx4 v126, s[94:95]
	s_add_u32 m0, s18, 0x800
	v_add_u32_e32 v126, 0x4080000, v120
	global_load_lds_dwordx4 v126, s[94:95]
	s_add_u32 m0, s18, 0xc00
	v_add_u32_e32 v126, 0x60c0000, v120
	global_load_lds_dwordx4 v126, s[94:95]
	s_add_u32 m0, s18, 0x1000
	v_add_u32_e32 v126, 0x8100000, v120
	global_load_lds_dwordx4 v126, s[94:95]
	s_add_u32 m0, s18, 0x1400
	v_add_u32_e32 v126, 0xa140000, v120
	global_load_lds_dwordx4 v126, s[94:95]
	s_add_u32 m0, s18, 0x1800
	v_add_u32_e32 v126, 0xc180000, v120
	global_load_lds_dwordx4 v126, s[94:95]
	s_add_u32 m0, s18, 0x1c00
	v_add_u32_e32 v126, 0xe1c0000, v120
	global_load_lds_dwordx4 v126, s[94:95]
	s_add_u32 m0, s18, 0x2000
	v_add_u32_e32 v126, 0x10200000, v120
	global_load_lds_dwordx4 v126, s[94:95]
	v_add_u32_e32 v120, 0x200000, v120
	v_min_u32_e32 v120, v120, v121
	s_add_u32 m0, s23, 0x0
	v_mov_b32_e32 v126, v120
	global_load_lds_dwordx4 v126, s[94:95]
	s_add_u32 m0, s23, 0x400
	v_add_u32_e32 v126, 0x2040000, v120
	global_load_lds_dwordx4 v126, s[94:95]
	s_add_u32 m0, s23, 0x800
	v_add_u32_e32 v126, 0x4080000, v120
	global_load_lds_dwordx4 v126, s[94:95]
	s_add_u32 m0, s23, 0xc00
	v_add_u32_e32 v126, 0x60c0000, v120
	global_load_lds_dwordx4 v126, s[94:95]
	s_add_u32 m0, s23, 0x1000
	v_add_u32_e32 v126, 0x8100000, v120
	global_load_lds_dwordx4 v126, s[94:95]
	s_add_u32 m0, s23, 0x1400
	v_add_u32_e32 v126, 0xa140000, v120
	global_load_lds_dwordx4 v126, s[94:95]
	s_add_u32 m0, s23, 0x1800
	v_add_u32_e32 v126, 0xc180000, v120
	global_load_lds_dwordx4 v126, s[94:95]
	s_add_u32 m0, s23, 0x1c00
	v_add_u32_e32 v126, 0xe1c0000, v120
	global_load_lds_dwordx4 v126, s[94:95]
	s_add_u32 m0, s23, 0x2000
	v_add_u32_e32 v126, 0x10200000, v120
	global_load_lds_dwordx4 v126, s[94:95]
	v_add_u32_e32 v120, 0x200000, v120
	v_min_u32_e32 v120, v120, v121
	s_waitcnt vmcnt(9)
	ds_read_b128 v[0:3], v125 offset:0
	ds_read_b128 v[4:7], v125 offset:1024
	ds_read_b128 v[8:11], v125 offset:2048
	ds_read_b128 v[12:15], v125 offset:3072
	ds_read_b128 v[16:19], v125 offset:4096
	ds_read_b128 v[20:23], v125 offset:5120
	ds_read_b128 v[24:27], v125 offset:6144
	ds_read_b128 v[28:31], v125 offset:7168
	ds_read_b128 v[64:67], v125 offset:8192
	s_waitcnt lgkmcnt(0)
	v_lshlrev_b32_e32 v64, 2, v64
	v_lshlrev_b32_e32 v65, 2, v65
	v_lshlrev_b32_e32 v66, 2, v66
	v_lshlrev_b32_e32 v67, 2, v67
	global_load_dword v68, v64, s[24:25]
	global_load_dword v69, v65, s[24:25]
	global_load_dword v70, v66, s[24:25]
	global_load_dword v71, v67, s[24:25]
	global_load_dword v72, v64, s[26:27]
	global_load_dword v73, v65, s[26:27]
	global_load_dword v74, v66, s[26:27]
	global_load_dword v75, v67, s[26:27]
	global_load_dwordx4 v[84:87], v122, s[94:95]
	v_add_u32_e32 v122, 0x200000, v122
	v_min_u32_e32 v122, v122, v123
	s_add_u32 m0, s18, 0x0
	v_mov_b32_e32 v126, v120
	global_load_lds_dwordx4 v126, s[94:95]
	s_add_u32 m0, s18, 0x400
	v_add_u32_e32 v126, 0x2040000, v120
	global_load_lds_dwordx4 v126, s[94:95]
	s_add_u32 m0, s18, 0x800
	v_add_u32_e32 v126, 0x4080000, v120
	global_load_lds_dwordx4 v126, s[94:95]
	s_add_u32 m0, s18, 0xc00
	v_add_u32_e32 v126, 0x60c0000, v120
	global_load_lds_dwordx4 v126, s[94:95]
	s_add_u32 m0, s18, 0x1000
	v_add_u32_e32 v126, 0x8100000, v120
	global_load_lds_dwordx4 v126, s[94:95]
	s_add_u32 m0, s18, 0x1400
	v_add_u32_e32 v126, 0xa140000, v120
	global_load_lds_dwordx4 v126, s[94:95]
	s_add_u32 m0, s18, 0x1800
	v_add_u32_e32 v126, 0xc180000, v120
	global_load_lds_dwordx4 v126, s[94:95]
	s_add_u32 m0, s18, 0x1c00
	v_add_u32_e32 v126, 0xe1c0000, v120
	global_load_lds_dwordx4 v126, s[94:95]
	s_add_u32 m0, s18, 0x2000
	v_add_u32_e32 v126, 0x10200000, v120
	global_load_lds_dwordx4 v126, s[94:95]
	v_add_u32_e32 v120, 0x200000, v120
	v_min_u32_e32 v120, v120, v121
	global_load_dword v137, v124, s[94:95]
	s_mov_b32 s17, 0
	s_waitcnt vmcnt(19)

.Lact1_done:
	s_waitcnt vmcnt(0) lgkmcnt(0)
.LBB0_1135:
	s_or_b64 exec, exec, s[0:1]
	s_waitcnt vmcnt(0) lgkmcnt(0)
	s_barrier
	s_mov_b64 s[0:1], exec
	v_readlane_b32 s2, v252, 31
	v_readlane_b32 s3, v252, 32
	s_and_b64 s[2:3], s[0:1], s[2:3]
	s_mov_b64 exec, s[2:3]
	s_cbranch_execz .LBB0_1141
	s_mov_b64 s[2:3], exec
	buffer_wbl2 sc1
	s_waitcnt vmcnt(0)
	s_waitcnt vmcnt(0)
	v_mbcnt_lo_u32_b32 v0, s2, 0
	v_mbcnt_hi_u32_b32 v0, s3, v0
	v_cmp_eq_u32_e32 vcc, 0, v0
	s_and_saveexec_b64 s[4:5], vcc
	s_cbranch_execz .LBB0_1138
	s_bcnt1_i32_b64 s2, s[2:3]
	s_and_b32 s98, s88, 7
	s_lshl_b32 s98, s98, 8
	s_add_u32 s98, s98, 0x3c6f0000
	v_mov_b32_e32 v0, s98
	v_mov_b32_e32 v1, s2
	global_atomic_add v1, v0, v1, s[94:95] sc0
